# grid barrier: XCD leader publishes its per-XCD generation word before its own acquire invalidate (followers released earlier), on top of static leading-half priority
# baseline (speedup 1.0000x reference)
.LBB0_868:
	s_or_b64 exec, exec, s[6:7]
	v_readlane_b32 s2, v254, 11
	v_readlane_b32 s3, v254, 12
	v_mov_b32_e32 v0, 1
	s_nop 4
	global_atomic_add v141, v0, s[2:3]
	s_waitcnt vmcnt(0)
	buffer_inv sc1
	s_waitcnt vmcnt(0)
